# sel score loops: MFMA-VALU interleave inside each 32-key tile (chunk A MFMAs, chunk B MFMAs with chunk A reduction in their shadow, then chunk B reduction; separate accumulators, no MFMA-to-VALU nops)
# speedup vs baseline: 1.0009x; 1.0009x over previous
.LBB0_820:
	s_add_i32 s40, s8, -3
	s_min_i32 s9, s40, s7
	s_lshl_b32 s98, s9, 15
	s_waitcnt vmcnt(12)
	v_lshl_add_u64 v[60:61], v[244:245], 0, s[98:99]
	global_load_dwordx4 v[88:91], v[60:61], off
	global_load_dwordx4 v[92:95], v[60:61], off offset:1024
	global_load_dwordx4 v[56:59], v[60:61], off offset:2048
	s_nop 0
	global_load_dwordx4 v[60:63], v[60:61], off offset:3072
	v_add_u32_e32 v103, v178, v98
	s_waitcnt vmcnt(15)
	ds_write_b128 v103, v[64:67]
	s_waitcnt vmcnt(14)
	ds_write_b128 v103, v[68:71] offset:1152
	v_add_u32_e32 v107, v179, v96
	ds_read_b128 v[64:67], v107
	ds_read_b128 v[68:71], v107 offset:64
	s_waitcnt vmcnt(13)
	ds_write_b128 v103, v[32:35]
	s_waitcnt vmcnt(12)
	ds_write_b128 v103, v[36:39] offset:1152
	ds_read_b128 v[32:35], v107
	ds_read_b128 v[36:39], v107 offset:64
	s_waitcnt lgkmcnt(4)
	v_mfma_f32_16x16x32_bf16 v[208:211], v[0:3], v[64:67], 0
	v_mfma_f32_16x16x32_bf16 v[212:215], v[8:11], v[64:67], 0
	v_mfma_f32_16x16x32_bf16 v[216:219], v[16:19], v[64:67], 0
	v_mfma_f32_16x16x32_bf16 v[220:223], v[24:27], v[64:67], 0
	v_mfma_f32_16x16x32_bf16 v[208:211], v[4:7], v[68:71], v[208:211]
	v_mfma_f32_16x16x32_bf16 v[212:215], v[12:15], v[68:71], v[212:215]
	v_mfma_f32_16x16x32_bf16 v[216:219], v[20:23], v[68:71], v[216:219]
	v_mfma_f32_16x16x32_bf16 v[220:223], v[28:31], v[68:71], v[220:223]
	s_waitcnt lgkmcnt(0)
	v_mfma_f32_16x16x32_bf16 v[224:227], v[0:3], v[32:35], 0
	v_mfma_f32_16x16x32_bf16 v[228:231], v[8:11], v[32:35], 0
	v_mfma_f32_16x16x32_bf16 v[232:235], v[16:19], v[32:35], 0
	v_mfma_f32_16x16x32_bf16 v[236:239], v[24:27], v[32:35], 0
	v_max_f32_e32 v208, 0, v208
	v_max_f32_e32 v212, 0, v212
	v_fma_f32 v208, v162, v208, 0
	v_fma_f32 v212, v166, v212, 0
	v_max_f32_e32 v209, 0, v209
	v_max_f32_e32 v213, 0, v213
	v_fmac_f32_e32 v208, v163, v209
	v_fmac_f32_e32 v212, v167, v213
	v_mfma_f32_16x16x32_bf16 v[224:227], v[4:7], v[36:39], v[224:227]
	v_max_f32_e32 v210, 0, v210
	v_max_f32_e32 v214, 0, v214
	v_fmac_f32_e32 v208, v164, v210
	v_fmac_f32_e32 v212, v168, v214
	v_max_f32_e32 v211, 0, v211
	v_max_f32_e32 v215, 0, v215
	v_fmac_f32_e32 v208, v165, v211
	v_fmac_f32_e32 v212, v169, v215
	v_mfma_f32_16x16x32_bf16 v[228:231], v[12:15], v[36:39], v[228:231]
	v_add_f32_e32 v208, v208, v212
	ds_write_b32 v99, v208
	v_max_f32_e32 v216, 0, v216
	v_max_f32_e32 v220, 0, v220
	v_fma_f32 v216, v170, v216, 0
	v_fma_f32 v220, v174, v220, 0
	v_max_f32_e32 v217, 0, v217
	v_max_f32_e32 v221, 0, v221
	v_mfma_f32_16x16x32_bf16 v[232:235], v[20:23], v[36:39], v[232:235]
	v_fmac_f32_e32 v216, v171, v217
	v_fmac_f32_e32 v220, v175, v221
	v_max_f32_e32 v218, 0, v218
	v_max_f32_e32 v222, 0, v222
	v_fmac_f32_e32 v216, v172, v218
	v_fmac_f32_e32 v220, v176, v222
	v_max_f32_e32 v219, 0, v219
	v_max_f32_e32 v223, 0, v223
	v_mfma_f32_16x16x32_bf16 v[236:239], v[28:31], v[36:39], v[236:239]
	v_fmac_f32_e32 v216, v173, v219
	v_fmac_f32_e32 v220, v177, v223
	v_add_f32_e32 v216, v216, v220
	ds_write_b32 v246, v216
	v_max_f32_e32 v224, 0, v224
	v_max_f32_e32 v228, 0, v228
	v_fma_f32 v224, v162, v224, 0
	v_fma_f32 v228, v166, v228, 0
	v_max_f32_e32 v225, 0, v225
	v_max_f32_e32 v229, 0, v229
	v_fmac_f32_e32 v224, v163, v225
	v_fmac_f32_e32 v228, v167, v229
	v_max_f32_e32 v226, 0, v226
	v_max_f32_e32 v230, 0, v230
	v_fmac_f32_e32 v224, v164, v226
	v_fmac_f32_e32 v228, v168, v230
	v_max_f32_e32 v227, 0, v227
	v_max_f32_e32 v231, 0, v231
	v_fmac_f32_e32 v224, v165, v227
	v_fmac_f32_e32 v228, v169, v231
	v_add_f32_e32 v224, v224, v228
	ds_write_b32 v99, v224 offset:64
	v_max_f32_e32 v232, 0, v232
	v_max_f32_e32 v236, 0, v236
	v_fma_f32 v232, v170, v232, 0
	v_fma_f32 v236, v174, v236, 0
	v_max_f32_e32 v233, 0, v233
	v_max_f32_e32 v237, 0, v237
	v_fmac_f32_e32 v232, v171, v233
	v_fmac_f32_e32 v236, v175, v237
	v_max_f32_e32 v234, 0, v234
	v_max_f32_e32 v238, 0, v238
	v_fmac_f32_e32 v232, v172, v234
	v_fmac_f32_e32 v236, v176, v238
	v_max_f32_e32 v235, 0, v235
	v_max_f32_e32 v239, 0, v239
	v_fmac_f32_e32 v232, v173, v235
	v_fmac_f32_e32 v236, v177, v239
	v_add_f32_e32 v232, v232, v236
	ds_write_b32 v246, v232 offset:64
	s_add_i32 s9, s8, -2
	s_min_i32 s57, s9, s7
	s_lshl_b32 s98, s57, 15
	v_lshl_add_u64 v[36:37], v[244:245], 0, s[98:99]
	global_load_dwordx4 v[64:67], v[36:37], off
	global_load_dwordx4 v[68:71], v[36:37], off offset:1024
	global_load_dwordx4 v[32:35], v[36:37], off offset:2048
	s_nop 0
	global_load_dwordx4 v[36:39], v[36:37], off offset:3072
	s_add_i32 s57, s8, -5
	s_cmp_ge_i32 s57, s6
	s_cbranch_scc1 .LBB0_822
	s_waitcnt vmcnt(15)
	ds_write_b128 v103, v[72:75]
	s_waitcnt vmcnt(14)
	ds_write_b128 v103, v[76:79] offset:1152
	ds_read_b128 v[72:75], v107
	ds_read_b128 v[76:79], v107 offset:64
	s_waitcnt vmcnt(13)
	ds_write_b128 v103, v[40:43]
	s_waitcnt vmcnt(12)
	ds_write_b128 v103, v[44:47] offset:1152
	ds_read_b128 v[40:43], v107
	ds_read_b128 v[44:47], v107 offset:64
	s_waitcnt lgkmcnt(4)
	v_mfma_f32_16x16x32_bf16 v[208:211], v[0:3], v[72:75], 0
	v_mfma_f32_16x16x32_bf16 v[212:215], v[8:11], v[72:75], 0
	v_mfma_f32_16x16x32_bf16 v[216:219], v[16:19], v[72:75], 0
	v_mfma_f32_16x16x32_bf16 v[220:223], v[24:27], v[72:75], 0
	v_mfma_f32_16x16x32_bf16 v[208:211], v[4:7], v[76:79], v[208:211]
	v_mfma_f32_16x16x32_bf16 v[212:215], v[12:15], v[76:79], v[212:215]
	v_mfma_f32_16x16x32_bf16 v[216:219], v[20:23], v[76:79], v[216:219]
	v_mfma_f32_16x16x32_bf16 v[220:223], v[28:31], v[76:79], v[220:223]
	s_waitcnt lgkmcnt(0)
	v_mfma_f32_16x16x32_bf16 v[224:227], v[0:3], v[40:43], 0
	v_mfma_f32_16x16x32_bf16 v[228:231], v[8:11], v[40:43], 0
	v_mfma_f32_16x16x32_bf16 v[232:235], v[16:19], v[40:43], 0
	v_mfma_f32_16x16x32_bf16 v[236:239], v[24:27], v[40:43], 0
	v_max_f32_e32 v208, 0, v208
	v_max_f32_e32 v212, 0, v212
	v_fma_f32 v208, v162, v208, 0
	v_fma_f32 v212, v166, v212, 0
	v_max_f32_e32 v209, 0, v209
	v_max_f32_e32 v213, 0, v213
	v_fmac_f32_e32 v208, v163, v209
	v_fmac_f32_e32 v212, v167, v213
	v_mfma_f32_16x16x32_bf16 v[224:227], v[4:7], v[44:47], v[224:227]
	v_max_f32_e32 v210, 0, v210
	v_max_f32_e32 v214, 0, v214
	v_fmac_f32_e32 v208, v164, v210
	v_fmac_f32_e32 v212, v168, v214
	v_max_f32_e32 v211, 0, v211
	v_max_f32_e32 v215, 0, v215
	v_fmac_f32_e32 v208, v165, v211
	v_fmac_f32_e32 v212, v169, v215
	v_mfma_f32_16x16x32_bf16 v[228:231], v[12:15], v[44:47], v[228:231]
	v_add_f32_e32 v208, v208, v212
	ds_write_b32 v99, v208 offset:1024
	v_max_f32_e32 v216, 0, v216
	v_max_f32_e32 v220, 0, v220
	v_fma_f32 v216, v170, v216, 0
	v_fma_f32 v220, v174, v220, 0
	v_max_f32_e32 v217, 0, v217
	v_max_f32_e32 v221, 0, v221
	v_mfma_f32_16x16x32_bf16 v[232:235], v[20:23], v[44:47], v[232:235]
	v_fmac_f32_e32 v216, v171, v217
	v_fmac_f32_e32 v220, v175, v221
	v_max_f32_e32 v218, 0, v218
	v_max_f32_e32 v222, 0, v222
	v_fmac_f32_e32 v216, v172, v218
	v_fmac_f32_e32 v220, v176, v222
	v_max_f32_e32 v219, 0, v219
	v_max_f32_e32 v223, 0, v223
	v_mfma_f32_16x16x32_bf16 v[236:239], v[28:31], v[44:47], v[236:239]
	v_fmac_f32_e32 v216, v173, v219
	v_fmac_f32_e32 v220, v177, v223
	v_add_f32_e32 v216, v216, v220
	ds_write_b32 v246, v216 offset:1024
	v_max_f32_e32 v224, 0, v224
	v_max_f32_e32 v228, 0, v228
	v_fma_f32 v224, v162, v224, 0
	v_fma_f32 v228, v166, v228, 0
	v_max_f32_e32 v225, 0, v225
	v_max_f32_e32 v229, 0, v229
	v_fmac_f32_e32 v224, v163, v225
	v_fmac_f32_e32 v228, v167, v229
	v_max_f32_e32 v226, 0, v226
	v_max_f32_e32 v230, 0, v230
	v_fmac_f32_e32 v224, v164, v226
	v_fmac_f32_e32 v228, v168, v230
	v_max_f32_e32 v227, 0, v227
	v_max_f32_e32 v231, 0, v231
	v_fmac_f32_e32 v224, v165, v227
	v_fmac_f32_e32 v228, v169, v231
	v_add_f32_e32 v224, v224, v228
	ds_write_b32 v99, v224 offset:1088
	v_max_f32_e32 v232, 0, v232
	v_max_f32_e32 v236, 0, v236
	v_fma_f32 v232, v170, v232, 0
	v_fma_f32 v236, v174, v236, 0
	v_max_f32_e32 v233, 0, v233
	v_max_f32_e32 v237, 0, v237
	v_fmac_f32_e32 v232, v171, v233
	v_fmac_f32_e32 v236, v175, v237
	v_max_f32_e32 v234, 0, v234
	v_max_f32_e32 v238, 0, v238
	v_fmac_f32_e32 v232, v172, v234
	v_fmac_f32_e32 v236, v176, v238
	v_max_f32_e32 v235, 0, v235
	v_max_f32_e32 v239, 0, v239
	v_fmac_f32_e32 v232, v173, v235
	v_fmac_f32_e32 v236, v177, v239
	v_add_f32_e32 v232, v232, v236
	ds_write_b32 v246, v232 offset:1088
.LBB0_822:
	s_add_i32 s57, s8, -1
	s_min_i32 s57, s57, s7
	s_lshl_b32 s98, s57, 15
	s_waitcnt vmcnt(12)
	v_lshl_add_u64 v[44:45], v[244:245], 0, s[98:99]
	global_load_dwordx4 v[72:75], v[44:45], off
	global_load_dwordx4 v[76:79], v[44:45], off offset:1024
	global_load_dwordx4 v[40:43], v[44:45], off offset:2048
	s_nop 0
	global_load_dwordx4 v[44:47], v[44:45], off offset:3072
	s_add_i32 s57, s8, -4
	s_cmp_ge_i32 s57, s6
	s_cbranch_scc1 .LBB0_824
	s_waitcnt vmcnt(15)
	ds_write_b128 v103, v[80:83]
	s_waitcnt vmcnt(14)
	ds_write_b128 v103, v[84:87] offset:1152
	ds_read_b128 v[80:83], v107
	ds_read_b128 v[84:87], v107 offset:64
	s_waitcnt vmcnt(13)
	ds_write_b128 v103, v[48:51]
	s_waitcnt vmcnt(12)
	ds_write_b128 v103, v[52:55] offset:1152
	ds_read_b128 v[48:51], v107
	ds_read_b128 v[52:55], v107 offset:64
	s_waitcnt lgkmcnt(4)
	v_mfma_f32_16x16x32_bf16 v[208:211], v[0:3], v[80:83], 0
	v_mfma_f32_16x16x32_bf16 v[212:215], v[8:11], v[80:83], 0
	v_mfma_f32_16x16x32_bf16 v[216:219], v[16:19], v[80:83], 0
	v_mfma_f32_16x16x32_bf16 v[220:223], v[24:27], v[80:83], 0
	v_mfma_f32_16x16x32_bf16 v[208:211], v[4:7], v[84:87], v[208:211]
	v_mfma_f32_16x16x32_bf16 v[212:215], v[12:15], v[84:87], v[212:215]
	v_mfma_f32_16x16x32_bf16 v[216:219], v[20:23], v[84:87], v[216:219]
	v_mfma_f32_16x16x32_bf16 v[220:223], v[28:31], v[84:87], v[220:223]
	s_waitcnt lgkmcnt(0)
	v_mfma_f32_16x16x32_bf16 v[224:227], v[0:3], v[48:51], 0
	v_mfma_f32_16x16x32_bf16 v[228:231], v[8:11], v[48:51], 0
	v_mfma_f32_16x16x32_bf16 v[232:235], v[16:19], v[48:51], 0
	v_mfma_f32_16x16x32_bf16 v[236:239], v[24:27], v[48:51], 0
	v_max_f32_e32 v208, 0, v208
	v_max_f32_e32 v212, 0, v212
	v_fma_f32 v208, v162, v208, 0
	v_fma_f32 v212, v166, v212, 0
	v_max_f32_e32 v209, 0, v209
	v_max_f32_e32 v213, 0, v213
	v_fmac_f32_e32 v208, v163, v209
	v_fmac_f32_e32 v212, v167, v213
	v_mfma_f32_16x16x32_bf16 v[224:227], v[4:7], v[52:55], v[224:227]
	v_max_f32_e32 v210, 0, v210
	v_max_f32_e32 v214, 0, v214
	v_fmac_f32_e32 v208, v164, v210
	v_fmac_f32_e32 v212, v168, v214
	v_max_f32_e32 v211, 0, v211
	v_max_f32_e32 v215, 0, v215
	v_fmac_f32_e32 v208, v165, v211
	v_fmac_f32_e32 v212, v169, v215
	v_mfma_f32_16x16x32_bf16 v[228:231], v[12:15], v[52:55], v[228:231]
	v_add_f32_e32 v208, v208, v212
	ds_write_b32 v99, v208 offset:2048
	v_max_f32_e32 v216, 0, v216
	v_max_f32_e32 v220, 0, v220
	v_fma_f32 v216, v170, v216, 0
	v_fma_f32 v220, v174, v220, 0
	v_max_f32_e32 v217, 0, v217
	v_max_f32_e32 v221, 0, v221
	v_mfma_f32_16x16x32_bf16 v[232:235], v[20:23], v[52:55], v[232:235]
	v_fmac_f32_e32 v216, v171, v217
	v_fmac_f32_e32 v220, v175, v221
	v_max_f32_e32 v218, 0, v218
	v_max_f32_e32 v222, 0, v222
	v_fmac_f32_e32 v216, v172, v218
	v_fmac_f32_e32 v220, v176, v222
	v_max_f32_e32 v219, 0, v219
	v_max_f32_e32 v223, 0, v223
	v_mfma_f32_16x16x32_bf16 v[236:239], v[28:31], v[52:55], v[236:239]
	v_fmac_f32_e32 v216, v173, v219
	v_fmac_f32_e32 v220, v177, v223
	v_add_f32_e32 v216, v216, v220
	ds_write_b32 v246, v216 offset:2048
	v_max_f32_e32 v224, 0, v224
	v_max_f32_e32 v228, 0, v228
	v_fma_f32 v224, v162, v224, 0
	v_fma_f32 v228, v166, v228, 0
	v_max_f32_e32 v225, 0, v225
	v_max_f32_e32 v229, 0, v229
	v_fmac_f32_e32 v224, v163, v225
	v_fmac_f32_e32 v228, v167, v229
	v_max_f32_e32 v226, 0, v226
	v_max_f32_e32 v230, 0, v230
	v_fmac_f32_e32 v224, v164, v226
	v_fmac_f32_e32 v228, v168, v230
	v_max_f32_e32 v227, 0, v227
	v_max_f32_e32 v231, 0, v231
	v_fmac_f32_e32 v224, v165, v227
	v_fmac_f32_e32 v228, v169, v231
	v_add_f32_e32 v224, v224, v228
	ds_write_b32 v99, v224 offset:2112
	v_max_f32_e32 v232, 0, v232
	v_max_f32_e32 v236, 0, v236
	v_fma_f32 v232, v170, v232, 0
	v_fma_f32 v236, v174, v236, 0
	v_max_f32_e32 v233, 0, v233
	v_max_f32_e32 v237, 0, v237
	v_fmac_f32_e32 v232, v171, v233
	v_fmac_f32_e32 v236, v175, v237
	v_max_f32_e32 v234, 0, v234
	v_max_f32_e32 v238, 0, v238
	v_fmac_f32_e32 v232, v172, v234
	v_fmac_f32_e32 v236, v176, v238
	v_max_f32_e32 v235, 0, v235
	v_max_f32_e32 v239, 0, v239
	v_fmac_f32_e32 v232, v173, v235
	v_fmac_f32_e32 v236, v177, v239
	v_add_f32_e32 v232, v232, v236
	ds_write_b32 v246, v232 offset:2112
.LBB0_824:
	s_min_i32 s57, s8, s7
	s_lshl_b32 s98, s57, 15
	s_cmp_ge_i32 s40, s6
	s_waitcnt vmcnt(12)
	v_lshl_add_u64 v[52:53], v[244:245], 0, s[98:99]
	global_load_dwordx4 v[80:83], v[52:53], off
	global_load_dwordx4 v[84:87], v[52:53], off offset:1024
	global_load_dwordx4 v[48:51], v[52:53], off offset:2048
	s_nop 0
	global_load_dwordx4 v[52:55], v[52:53], off offset:3072
	s_cbranch_scc1 .LBB0_819
	s_waitcnt vmcnt(15)
	ds_write_b128 v103, v[88:91]
	s_waitcnt vmcnt(14)
	ds_write_b128 v103, v[92:95] offset:1152
	ds_read_b128 v[88:91], v107
	ds_read_b128 v[92:95], v107 offset:64
	s_waitcnt vmcnt(13)
	ds_write_b128 v103, v[56:59]
	s_waitcnt vmcnt(12)
	ds_write_b128 v103, v[60:63] offset:1152
	ds_read_b128 v[56:59], v107
	ds_read_b128 v[60:63], v107 offset:64
	s_waitcnt lgkmcnt(4)
	v_mfma_f32_16x16x32_bf16 v[208:211], v[0:3], v[88:91], 0
	v_mfma_f32_16x16x32_bf16 v[212:215], v[8:11], v[88:91], 0
	v_mfma_f32_16x16x32_bf16 v[216:219], v[16:19], v[88:91], 0
	v_mfma_f32_16x16x32_bf16 v[220:223], v[24:27], v[88:91], 0
	v_mfma_f32_16x16x32_bf16 v[208:211], v[4:7], v[92:95], v[208:211]
	v_mfma_f32_16x16x32_bf16 v[212:215], v[12:15], v[92:95], v[212:215]
	v_mfma_f32_16x16x32_bf16 v[216:219], v[20:23], v[92:95], v[216:219]
	v_mfma_f32_16x16x32_bf16 v[220:223], v[28:31], v[92:95], v[220:223]
	s_waitcnt lgkmcnt(0)
	v_mfma_f32_16x16x32_bf16 v[224:227], v[0:3], v[56:59], 0
	v_mfma_f32_16x16x32_bf16 v[228:231], v[8:11], v[56:59], 0
	v_mfma_f32_16x16x32_bf16 v[232:235], v[16:19], v[56:59], 0
	v_mfma_f32_16x16x32_bf16 v[236:239], v[24:27], v[56:59], 0
	v_max_f32_e32 v208, 0, v208
	v_max_f32_e32 v212, 0, v212
	v_fma_f32 v208, v162, v208, 0
	v_fma_f32 v212, v166, v212, 0
	v_max_f32_e32 v209, 0, v209
	v_max_f32_e32 v213, 0, v213
	v_fmac_f32_e32 v208, v163, v209
	v_fmac_f32_e32 v212, v167, v213
	v_mfma_f32_16x16x32_bf16 v[224:227], v[4:7], v[60:63], v[224:227]
	v_max_f32_e32 v210, 0, v210
	v_max_f32_e32 v214, 0, v214
	v_fmac_f32_e32 v208, v164, v210
	v_fmac_f32_e32 v212, v168, v214
	v_max_f32_e32 v211, 0, v211
	v_max_f32_e32 v215, 0, v215
	v_fmac_f32_e32 v208, v165, v211
	v_fmac_f32_e32 v212, v169, v215
	v_mfma_f32_16x16x32_bf16 v[228:231], v[12:15], v[60:63], v[228:231]
	v_add_f32_e32 v208, v208, v212
	ds_write_b32 v99, v208 offset:3072
	v_max_f32_e32 v216, 0, v216
	v_max_f32_e32 v220, 0, v220
	v_fma_f32 v216, v170, v216, 0
	v_fma_f32 v220, v174, v220, 0
	v_max_f32_e32 v217, 0, v217
	v_max_f32_e32 v221, 0, v221
	v_mfma_f32_16x16x32_bf16 v[232:235], v[20:23], v[60:63], v[232:235]
	v_fmac_f32_e32 v216, v171, v217
	v_fmac_f32_e32 v220, v175, v221
	v_max_f32_e32 v218, 0, v218
	v_max_f32_e32 v222, 0, v222
	v_fmac_f32_e32 v216, v172, v218
	v_fmac_f32_e32 v220, v176, v222
	v_max_f32_e32 v219, 0, v219
	v_max_f32_e32 v223, 0, v223
	v_mfma_f32_16x16x32_bf16 v[236:239], v[28:31], v[60:63], v[236:239]
	v_fmac_f32_e32 v216, v173, v219
	v_fmac_f32_e32 v220, v177, v223
	v_add_f32_e32 v216, v216, v220
	ds_write_b32 v246, v216 offset:3072
	v_max_f32_e32 v224, 0, v224
	v_max_f32_e32 v228, 0, v228
	v_fma_f32 v224, v162, v224, 0
	v_fma_f32 v228, v166, v228, 0
	v_max_f32_e32 v225, 0, v225
	v_max_f32_e32 v229, 0, v229
	v_fmac_f32_e32 v224, v163, v225
	v_fmac_f32_e32 v228, v167, v229
	v_max_f32_e32 v226, 0, v226
	v_max_f32_e32 v230, 0, v230
	v_fmac_f32_e32 v224, v164, v226
	v_fmac_f32_e32 v228, v168, v230
	v_max_f32_e32 v227, 0, v227
	v_max_f32_e32 v231, 0, v231
	v_fmac_f32_e32 v224, v165, v227
	v_fmac_f32_e32 v228, v169, v231
	v_add_f32_e32 v224, v224, v228
	ds_write_b32 v99, v224 offset:3136
	v_max_f32_e32 v232, 0, v232
	v_max_f32_e32 v236, 0, v236
	v_fma_f32 v232, v170, v232, 0
	v_fma_f32 v236, v174, v236, 0
	v_max_f32_e32 v233, 0, v233
	v_max_f32_e32 v237, 0, v237
	v_fmac_f32_e32 v232, v171, v233
	v_fmac_f32_e32 v236, v175, v237
	v_max_f32_e32 v234, 0, v234
	v_max_f32_e32 v238, 0, v238
	v_fmac_f32_e32 v232, v172, v234
	v_fmac_f32_e32 v236, v176, v238
	v_max_f32_e32 v235, 0, v235
	v_max_f32_e32 v239, 0, v239
	v_fmac_f32_e32 v232, v173, v235
	v_fmac_f32_e32 v236, v177, v239
	v_add_f32_e32 v232, v232, v236
	ds_write_b32 v246, v232 offset:3136
	s_branch .LBB0_819

.LBB0_834:
	s_add_i32 s40, s8, -3
	s_min_i32 s9, s40, s7
	s_lshl_b32 s98, s9, 15
	s_waitcnt vmcnt(12)
	v_lshl_add_u64 v[60:61], v[244:245], 0, s[98:99]
	global_load_dwordx4 v[88:91], v[60:61], off
	global_load_dwordx4 v[92:95], v[60:61], off offset:1024
	global_load_dwordx4 v[56:59], v[60:61], off offset:2048
	s_nop 0
	global_load_dwordx4 v[60:63], v[60:61], off offset:3072
	v_add_u32_e32 v103, v178, v98
	s_waitcnt vmcnt(15)
	ds_write_b128 v103, v[64:67]
	s_waitcnt vmcnt(14)
	ds_write_b128 v103, v[68:71] offset:1152
	v_add_u32_e32 v191, v179, v96
	ds_read_b128 v[64:67], v191
	ds_read_b128 v[68:71], v191 offset:64
	s_waitcnt vmcnt(13)
	ds_write_b128 v103, v[32:35]
	s_waitcnt vmcnt(12)
	ds_write_b128 v103, v[36:39] offset:1152
	ds_read_b128 v[32:35], v191
	ds_read_b128 v[36:39], v191 offset:64
	s_waitcnt lgkmcnt(4)
	v_mfma_f32_16x16x32_bf16 v[208:211], v[0:3], v[64:67], 0
	v_mfma_f32_16x16x32_bf16 v[212:215], v[8:11], v[64:67], 0
	v_mfma_f32_16x16x32_bf16 v[216:219], v[16:19], v[64:67], 0
	v_mfma_f32_16x16x32_bf16 v[220:223], v[24:27], v[64:67], 0
	v_mfma_f32_16x16x32_bf16 v[208:211], v[4:7], v[68:71], v[208:211]
	v_mfma_f32_16x16x32_bf16 v[212:215], v[12:15], v[68:71], v[212:215]
	v_mfma_f32_16x16x32_bf16 v[216:219], v[20:23], v[68:71], v[216:219]
	v_mfma_f32_16x16x32_bf16 v[220:223], v[28:31], v[68:71], v[220:223]
	s_waitcnt lgkmcnt(0)
	v_mfma_f32_16x16x32_bf16 v[224:227], v[0:3], v[32:35], 0
	v_mfma_f32_16x16x32_bf16 v[228:231], v[8:11], v[32:35], 0
	v_mfma_f32_16x16x32_bf16 v[232:235], v[16:19], v[32:35], 0
	v_mfma_f32_16x16x32_bf16 v[236:239], v[24:27], v[32:35], 0
	v_max_f32_e32 v208, 0, v208
	v_max_f32_e32 v212, 0, v212
	v_fma_f32 v208, v162, v208, 0
	v_fma_f32 v212, v166, v212, 0
	v_max_f32_e32 v209, 0, v209
	v_max_f32_e32 v213, 0, v213
	v_fmac_f32_e32 v208, v163, v209
	v_fmac_f32_e32 v212, v167, v213
	v_mfma_f32_16x16x32_bf16 v[224:227], v[4:7], v[36:39], v[224:227]
	v_max_f32_e32 v210, 0, v210
	v_max_f32_e32 v214, 0, v214
	v_fmac_f32_e32 v208, v164, v210
	v_fmac_f32_e32 v212, v168, v214
	v_max_f32_e32 v211, 0, v211
	v_max_f32_e32 v215, 0, v215
	v_fmac_f32_e32 v208, v165, v211
	v_fmac_f32_e32 v212, v169, v215
	v_mfma_f32_16x16x32_bf16 v[228:231], v[12:15], v[36:39], v[228:231]
	v_add_f32_e32 v208, v208, v212
	ds_write_b32 v180, v208
	v_max_f32_e32 v216, 0, v216
	v_max_f32_e32 v220, 0, v220
	v_fma_f32 v216, v170, v216, 0
	v_fma_f32 v220, v174, v220, 0
	v_max_f32_e32 v217, 0, v217
	v_max_f32_e32 v221, 0, v221
	v_mfma_f32_16x16x32_bf16 v[232:235], v[20:23], v[36:39], v[232:235]
	v_fmac_f32_e32 v216, v171, v217
	v_fmac_f32_e32 v220, v175, v221
	v_max_f32_e32 v218, 0, v218
	v_max_f32_e32 v222, 0, v222
	v_fmac_f32_e32 v216, v172, v218
	v_fmac_f32_e32 v220, v176, v222
	v_max_f32_e32 v219, 0, v219
	v_max_f32_e32 v223, 0, v223
	v_mfma_f32_16x16x32_bf16 v[236:239], v[28:31], v[36:39], v[236:239]
	v_fmac_f32_e32 v216, v173, v219
	v_fmac_f32_e32 v220, v177, v223
	v_add_f32_e32 v216, v216, v220
	ds_write_b32 v246, v216
	v_max_f32_e32 v224, 0, v224
	v_max_f32_e32 v228, 0, v228
	v_fma_f32 v224, v162, v224, 0
	v_fma_f32 v228, v166, v228, 0
	v_max_f32_e32 v225, 0, v225
	v_max_f32_e32 v229, 0, v229
	v_fmac_f32_e32 v224, v163, v225
	v_fmac_f32_e32 v228, v167, v229
	v_max_f32_e32 v226, 0, v226
	v_max_f32_e32 v230, 0, v230
	v_fmac_f32_e32 v224, v164, v226
	v_fmac_f32_e32 v228, v168, v230
	v_max_f32_e32 v227, 0, v227
	v_max_f32_e32 v231, 0, v231
	v_fmac_f32_e32 v224, v165, v227
	v_fmac_f32_e32 v228, v169, v231
	v_add_f32_e32 v224, v224, v228
	ds_write_b32 v180, v224 offset:64
	v_max_f32_e32 v232, 0, v232
	v_max_f32_e32 v236, 0, v236
	v_fma_f32 v232, v170, v232, 0
	v_fma_f32 v236, v174, v236, 0
	v_max_f32_e32 v233, 0, v233
	v_max_f32_e32 v237, 0, v237
	v_fmac_f32_e32 v232, v171, v233
	v_fmac_f32_e32 v236, v175, v237
	v_max_f32_e32 v234, 0, v234
	v_max_f32_e32 v238, 0, v238
	v_fmac_f32_e32 v232, v172, v234
	v_fmac_f32_e32 v236, v176, v238
	v_max_f32_e32 v235, 0, v235
	v_max_f32_e32 v239, 0, v239
	v_fmac_f32_e32 v232, v173, v235
	v_fmac_f32_e32 v236, v177, v239
	v_add_f32_e32 v232, v232, v236
	ds_write_b32 v246, v232 offset:64
	s_add_i32 s9, s8, -2
	s_min_i32 s57, s9, s7
	s_lshl_b32 s98, s57, 15
	v_lshl_add_u64 v[36:37], v[244:245], 0, s[98:99]
	global_load_dwordx4 v[64:67], v[36:37], off
	global_load_dwordx4 v[68:71], v[36:37], off offset:1024
	global_load_dwordx4 v[32:35], v[36:37], off offset:2048
	s_nop 0
	global_load_dwordx4 v[36:39], v[36:37], off offset:3072
	s_add_i32 s57, s8, -5
	s_cmp_ge_i32 s57, s6
	s_cbranch_scc1 .LBB0_836
	s_waitcnt vmcnt(15)
	ds_write_b128 v103, v[72:75]
	s_waitcnt vmcnt(14)
	ds_write_b128 v103, v[76:79] offset:1152
	ds_read_b128 v[72:75], v191
	ds_read_b128 v[76:79], v191 offset:64
	s_waitcnt vmcnt(13)
	ds_write_b128 v103, v[40:43]
	s_waitcnt vmcnt(12)
	ds_write_b128 v103, v[44:47] offset:1152
	ds_read_b128 v[40:43], v191
	ds_read_b128 v[44:47], v191 offset:64
	s_waitcnt lgkmcnt(4)
	v_mfma_f32_16x16x32_bf16 v[208:211], v[0:3], v[72:75], 0
	v_mfma_f32_16x16x32_bf16 v[212:215], v[8:11], v[72:75], 0
	v_mfma_f32_16x16x32_bf16 v[216:219], v[16:19], v[72:75], 0
	v_mfma_f32_16x16x32_bf16 v[220:223], v[24:27], v[72:75], 0
	v_mfma_f32_16x16x32_bf16 v[208:211], v[4:7], v[76:79], v[208:211]
	v_mfma_f32_16x16x32_bf16 v[212:215], v[12:15], v[76:79], v[212:215]
	v_mfma_f32_16x16x32_bf16 v[216:219], v[20:23], v[76:79], v[216:219]
	v_mfma_f32_16x16x32_bf16 v[220:223], v[28:31], v[76:79], v[220:223]
	s_waitcnt lgkmcnt(0)
	v_mfma_f32_16x16x32_bf16 v[224:227], v[0:3], v[40:43], 0
	v_mfma_f32_16x16x32_bf16 v[228:231], v[8:11], v[40:43], 0
	v_mfma_f32_16x16x32_bf16 v[232:235], v[16:19], v[40:43], 0
	v_mfma_f32_16x16x32_bf16 v[236:239], v[24:27], v[40:43], 0
	v_max_f32_e32 v208, 0, v208
	v_max_f32_e32 v212, 0, v212
	v_fma_f32 v208, v162, v208, 0
	v_fma_f32 v212, v166, v212, 0
	v_max_f32_e32 v209, 0, v209
	v_max_f32_e32 v213, 0, v213
	v_fmac_f32_e32 v208, v163, v209
	v_fmac_f32_e32 v212, v167, v213
	v_mfma_f32_16x16x32_bf16 v[224:227], v[4:7], v[44:47], v[224:227]
	v_max_f32_e32 v210, 0, v210
	v_max_f32_e32 v214, 0, v214
	v_fmac_f32_e32 v208, v164, v210
	v_fmac_f32_e32 v212, v168, v214
	v_max_f32_e32 v211, 0, v211
	v_max_f32_e32 v215, 0, v215
	v_fmac_f32_e32 v208, v165, v211
	v_fmac_f32_e32 v212, v169, v215
	v_mfma_f32_16x16x32_bf16 v[228:231], v[12:15], v[44:47], v[228:231]
	v_add_f32_e32 v208, v208, v212
	ds_write_b32 v180, v208 offset:1024
	v_max_f32_e32 v216, 0, v216
	v_max_f32_e32 v220, 0, v220
	v_fma_f32 v216, v170, v216, 0
	v_fma_f32 v220, v174, v220, 0
	v_max_f32_e32 v217, 0, v217
	v_max_f32_e32 v221, 0, v221
	v_mfma_f32_16x16x32_bf16 v[232:235], v[20:23], v[44:47], v[232:235]
	v_fmac_f32_e32 v216, v171, v217
	v_fmac_f32_e32 v220, v175, v221
	v_max_f32_e32 v218, 0, v218
	v_max_f32_e32 v222, 0, v222
	v_fmac_f32_e32 v216, v172, v218
	v_fmac_f32_e32 v220, v176, v222
	v_max_f32_e32 v219, 0, v219
	v_max_f32_e32 v223, 0, v223
	v_mfma_f32_16x16x32_bf16 v[236:239], v[28:31], v[44:47], v[236:239]
	v_fmac_f32_e32 v216, v173, v219
	v_fmac_f32_e32 v220, v177, v223
	v_add_f32_e32 v216, v216, v220
	ds_write_b32 v246, v216 offset:1024
	v_max_f32_e32 v224, 0, v224
	v_max_f32_e32 v228, 0, v228
	v_fma_f32 v224, v162, v224, 0
	v_fma_f32 v228, v166, v228, 0
	v_max_f32_e32 v225, 0, v225
	v_max_f32_e32 v229, 0, v229
	v_fmac_f32_e32 v224, v163, v225
	v_fmac_f32_e32 v228, v167, v229
	v_max_f32_e32 v226, 0, v226
	v_max_f32_e32 v230, 0, v230
	v_fmac_f32_e32 v224, v164, v226
	v_fmac_f32_e32 v228, v168, v230
	v_max_f32_e32 v227, 0, v227
	v_max_f32_e32 v231, 0, v231
	v_fmac_f32_e32 v224, v165, v227
	v_fmac_f32_e32 v228, v169, v231
	v_add_f32_e32 v224, v224, v228
	ds_write_b32 v180, v224 offset:1088
	v_max_f32_e32 v232, 0, v232
	v_max_f32_e32 v236, 0, v236
	v_fma_f32 v232, v170, v232, 0
	v_fma_f32 v236, v174, v236, 0
	v_max_f32_e32 v233, 0, v233
	v_max_f32_e32 v237, 0, v237
	v_fmac_f32_e32 v232, v171, v233
	v_fmac_f32_e32 v236, v175, v237
	v_max_f32_e32 v234, 0, v234
	v_max_f32_e32 v238, 0, v238
	v_fmac_f32_e32 v232, v172, v234
	v_fmac_f32_e32 v236, v176, v238
	v_max_f32_e32 v235, 0, v235
	v_max_f32_e32 v239, 0, v239
	v_fmac_f32_e32 v232, v173, v235
	v_fmac_f32_e32 v236, v177, v239
	v_add_f32_e32 v232, v232, v236
	ds_write_b32 v246, v232 offset:1088
.LBB0_836:
	s_add_i32 s57, s8, -1
	s_min_i32 s57, s57, s7
	s_lshl_b32 s98, s57, 15
	s_waitcnt vmcnt(12)
	v_lshl_add_u64 v[44:45], v[244:245], 0, s[98:99]
	global_load_dwordx4 v[72:75], v[44:45], off
	global_load_dwordx4 v[76:79], v[44:45], off offset:1024
	global_load_dwordx4 v[40:43], v[44:45], off offset:2048
	s_nop 0
	global_load_dwordx4 v[44:47], v[44:45], off offset:3072
	s_add_i32 s57, s8, -4
	s_cmp_ge_i32 s57, s6
	s_cbranch_scc1 .LBB0_838
	s_waitcnt vmcnt(15)
	ds_write_b128 v103, v[80:83]
	s_waitcnt vmcnt(14)
	ds_write_b128 v103, v[84:87] offset:1152
	ds_read_b128 v[80:83], v191
	ds_read_b128 v[84:87], v191 offset:64
	s_waitcnt vmcnt(13)
	ds_write_b128 v103, v[48:51]
	s_waitcnt vmcnt(12)
	ds_write_b128 v103, v[52:55] offset:1152
	ds_read_b128 v[48:51], v191
	ds_read_b128 v[52:55], v191 offset:64
	s_waitcnt lgkmcnt(4)
	v_mfma_f32_16x16x32_bf16 v[208:211], v[0:3], v[80:83], 0
	v_mfma_f32_16x16x32_bf16 v[212:215], v[8:11], v[80:83], 0
	v_mfma_f32_16x16x32_bf16 v[216:219], v[16:19], v[80:83], 0
	v_mfma_f32_16x16x32_bf16 v[220:223], v[24:27], v[80:83], 0
	v_mfma_f32_16x16x32_bf16 v[208:211], v[4:7], v[84:87], v[208:211]
	v_mfma_f32_16x16x32_bf16 v[212:215], v[12:15], v[84:87], v[212:215]
	v_mfma_f32_16x16x32_bf16 v[216:219], v[20:23], v[84:87], v[216:219]
	v_mfma_f32_16x16x32_bf16 v[220:223], v[28:31], v[84:87], v[220:223]
	s_waitcnt lgkmcnt(0)
	v_mfma_f32_16x16x32_bf16 v[224:227], v[0:3], v[48:51], 0
	v_mfma_f32_16x16x32_bf16 v[228:231], v[8:11], v[48:51], 0
	v_mfma_f32_16x16x32_bf16 v[232:235], v[16:19], v[48:51], 0
	v_mfma_f32_16x16x32_bf16 v[236:239], v[24:27], v[48:51], 0
	v_max_f32_e32 v208, 0, v208
	v_max_f32_e32 v212, 0, v212
	v_fma_f32 v208, v162, v208, 0
	v_fma_f32 v212, v166, v212, 0
	v_max_f32_e32 v209, 0, v209
	v_max_f32_e32 v213, 0, v213
	v_fmac_f32_e32 v208, v163, v209
	v_fmac_f32_e32 v212, v167, v213
	v_mfma_f32_16x16x32_bf16 v[224:227], v[4:7], v[52:55], v[224:227]
	v_max_f32_e32 v210, 0, v210
	v_max_f32_e32 v214, 0, v214
	v_fmac_f32_e32 v208, v164, v210
	v_fmac_f32_e32 v212, v168, v214
	v_max_f32_e32 v211, 0, v211
	v_max_f32_e32 v215, 0, v215
	v_fmac_f32_e32 v208, v165, v211
	v_fmac_f32_e32 v212, v169, v215
	v_mfma_f32_16x16x32_bf16 v[228:231], v[12:15], v[52:55], v[228:231]
	v_add_f32_e32 v208, v208, v212
	ds_write_b32 v180, v208 offset:2048
	v_max_f32_e32 v216, 0, v216
	v_max_f32_e32 v220, 0, v220
	v_fma_f32 v216, v170, v216, 0
	v_fma_f32 v220, v174, v220, 0
	v_max_f32_e32 v217, 0, v217
	v_max_f32_e32 v221, 0, v221
	v_mfma_f32_16x16x32_bf16 v[232:235], v[20:23], v[52:55], v[232:235]
	v_fmac_f32_e32 v216, v171, v217
	v_fmac_f32_e32 v220, v175, v221
	v_max_f32_e32 v218, 0, v218
	v_max_f32_e32 v222, 0, v222
	v_fmac_f32_e32 v216, v172, v218
	v_fmac_f32_e32 v220, v176, v222
	v_max_f32_e32 v219, 0, v219
	v_max_f32_e32 v223, 0, v223
	v_mfma_f32_16x16x32_bf16 v[236:239], v[28:31], v[52:55], v[236:239]
	v_fmac_f32_e32 v216, v173, v219
	v_fmac_f32_e32 v220, v177, v223
	v_add_f32_e32 v216, v216, v220
	ds_write_b32 v246, v216 offset:2048
	v_max_f32_e32 v224, 0, v224
	v_max_f32_e32 v228, 0, v228
	v_fma_f32 v224, v162, v224, 0
	v_fma_f32 v228, v166, v228, 0
	v_max_f32_e32 v225, 0, v225
	v_max_f32_e32 v229, 0, v229
	v_fmac_f32_e32 v224, v163, v225
	v_fmac_f32_e32 v228, v167, v229
	v_max_f32_e32 v226, 0, v226
	v_max_f32_e32 v230, 0, v230
	v_fmac_f32_e32 v224, v164, v226
	v_fmac_f32_e32 v228, v168, v230
	v_max_f32_e32 v227, 0, v227
	v_max_f32_e32 v231, 0, v231
	v_fmac_f32_e32 v224, v165, v227
	v_fmac_f32_e32 v228, v169, v231
	v_add_f32_e32 v224, v224, v228
	ds_write_b32 v180, v224 offset:2112
	v_max_f32_e32 v232, 0, v232
	v_max_f32_e32 v236, 0, v236
	v_fma_f32 v232, v170, v232, 0
	v_fma_f32 v236, v174, v236, 0
	v_max_f32_e32 v233, 0, v233
	v_max_f32_e32 v237, 0, v237
	v_fmac_f32_e32 v232, v171, v233
	v_fmac_f32_e32 v236, v175, v237
	v_max_f32_e32 v234, 0, v234
	v_max_f32_e32 v238, 0, v238
	v_fmac_f32_e32 v232, v172, v234
	v_fmac_f32_e32 v236, v176, v238
	v_max_f32_e32 v235, 0, v235
	v_max_f32_e32 v239, 0, v239
	v_fmac_f32_e32 v232, v173, v235
	v_fmac_f32_e32 v236, v177, v239
	v_add_f32_e32 v232, v232, v236
	ds_write_b32 v246, v232 offset:2112
.LBB0_838:
	s_min_i32 s57, s8, s7
	s_lshl_b32 s98, s57, 15
	s_cmp_ge_i32 s40, s6
	s_waitcnt vmcnt(12)
	v_lshl_add_u64 v[52:53], v[244:245], 0, s[98:99]
	global_load_dwordx4 v[80:83], v[52:53], off
	global_load_dwordx4 v[84:87], v[52:53], off offset:1024
	global_load_dwordx4 v[48:51], v[52:53], off offset:2048
	s_nop 0
	global_load_dwordx4 v[52:55], v[52:53], off offset:3072
	s_cbranch_scc1 .LBB0_833
	s_waitcnt vmcnt(15)
	ds_write_b128 v103, v[88:91]
	s_waitcnt vmcnt(14)
	ds_write_b128 v103, v[92:95] offset:1152
	ds_read_b128 v[88:91], v191
	ds_read_b128 v[92:95], v191 offset:64
	s_waitcnt vmcnt(13)
	ds_write_b128 v103, v[56:59]
	s_waitcnt vmcnt(12)
	ds_write_b128 v103, v[60:63] offset:1152
	ds_read_b128 v[56:59], v191
	ds_read_b128 v[60:63], v191 offset:64
	s_waitcnt lgkmcnt(4)
	v_mfma_f32_16x16x32_bf16 v[208:211], v[0:3], v[88:91], 0
	v_mfma_f32_16x16x32_bf16 v[212:215], v[8:11], v[88:91], 0
	v_mfma_f32_16x16x32_bf16 v[216:219], v[16:19], v[88:91], 0
	v_mfma_f32_16x16x32_bf16 v[220:223], v[24:27], v[88:91], 0
	v_mfma_f32_16x16x32_bf16 v[208:211], v[4:7], v[92:95], v[208:211]
	v_mfma_f32_16x16x32_bf16 v[212:215], v[12:15], v[92:95], v[212:215]
	v_mfma_f32_16x16x32_bf16 v[216:219], v[20:23], v[92:95], v[216:219]
	v_mfma_f32_16x16x32_bf16 v[220:223], v[28:31], v[92:95], v[220:223]
	s_waitcnt lgkmcnt(0)
	v_mfma_f32_16x16x32_bf16 v[224:227], v[0:3], v[56:59], 0
	v_mfma_f32_16x16x32_bf16 v[228:231], v[8:11], v[56:59], 0
	v_mfma_f32_16x16x32_bf16 v[232:235], v[16:19], v[56:59], 0
	v_mfma_f32_16x16x32_bf16 v[236:239], v[24:27], v[56:59], 0
	v_max_f32_e32 v208, 0, v208
	v_max_f32_e32 v212, 0, v212
	v_fma_f32 v208, v162, v208, 0
	v_fma_f32 v212, v166, v212, 0
	v_max_f32_e32 v209, 0, v209
	v_max_f32_e32 v213, 0, v213
	v_fmac_f32_e32 v208, v163, v209
	v_fmac_f32_e32 v212, v167, v213
	v_mfma_f32_16x16x32_bf16 v[224:227], v[4:7], v[60:63], v[224:227]
	v_max_f32_e32 v210, 0, v210
	v_max_f32_e32 v214, 0, v214
	v_fmac_f32_e32 v208, v164, v210
	v_fmac_f32_e32 v212, v168, v214
	v_max_f32_e32 v211, 0, v211
	v_max_f32_e32 v215, 0, v215
	v_fmac_f32_e32 v208, v165, v211
	v_fmac_f32_e32 v212, v169, v215
	v_mfma_f32_16x16x32_bf16 v[228:231], v[12:15], v[60:63], v[228:231]
	v_add_f32_e32 v208, v208, v212
	ds_write_b32 v180, v208 offset:3072
	v_max_f32_e32 v216, 0, v216
	v_max_f32_e32 v220, 0, v220
	v_fma_f32 v216, v170, v216, 0
	v_fma_f32 v220, v174, v220, 0
	v_max_f32_e32 v217, 0, v217
	v_max_f32_e32 v221, 0, v221
	v_mfma_f32_16x16x32_bf16 v[232:235], v[20:23], v[60:63], v[232:235]
	v_fmac_f32_e32 v216, v171, v217
	v_fmac_f32_e32 v220, v175, v221
	v_max_f32_e32 v218, 0, v218
	v_max_f32_e32 v222, 0, v222
	v_fmac_f32_e32 v216, v172, v218
	v_fmac_f32_e32 v220, v176, v222
	v_max_f32_e32 v219, 0, v219
	v_max_f32_e32 v223, 0, v223
	v_mfma_f32_16x16x32_bf16 v[236:239], v[28:31], v[60:63], v[236:239]
	v_fmac_f32_e32 v216, v173, v219
	v_fmac_f32_e32 v220, v177, v223
	v_add_f32_e32 v216, v216, v220
	ds_write_b32 v246, v216 offset:3072
	v_max_f32_e32 v224, 0, v224
	v_max_f32_e32 v228, 0, v228
	v_fma_f32 v224, v162, v224, 0
	v_fma_f32 v228, v166, v228, 0
	v_max_f32_e32 v225, 0, v225
	v_max_f32_e32 v229, 0, v229
	v_fmac_f32_e32 v224, v163, v225
	v_fmac_f32_e32 v228, v167, v229
	v_max_f32_e32 v226, 0, v226
	v_max_f32_e32 v230, 0, v230
	v_fmac_f32_e32 v224, v164, v226
	v_fmac_f32_e32 v228, v168, v230
	v_max_f32_e32 v227, 0, v227
	v_max_f32_e32 v231, 0, v231
	v_fmac_f32_e32 v224, v165, v227
	v_fmac_f32_e32 v228, v169, v231
	v_add_f32_e32 v224, v224, v228
	ds_write_b32 v180, v224 offset:3136
	v_max_f32_e32 v232, 0, v232
	v_max_f32_e32 v236, 0, v236
	v_fma_f32 v232, v170, v232, 0
	v_fma_f32 v236, v174, v236, 0
	v_max_f32_e32 v233, 0, v233
	v_max_f32_e32 v237, 0, v237
	v_fmac_f32_e32 v232, v171, v233
	v_fmac_f32_e32 v236, v175, v237
	v_max_f32_e32 v234, 0, v234
	v_max_f32_e32 v238, 0, v238
	v_fmac_f32_e32 v232, v172, v234
	v_fmac_f32_e32 v236, v176, v238
	v_max_f32_e32 v235, 0, v235
	v_max_f32_e32 v239, 0, v239
	v_fmac_f32_e32 v232, v173, v235
	v_fmac_f32_e32 v236, v177, v239
	v_add_f32_e32 v232, v232, v236
	ds_write_b32 v246, v232 offset:3136
	s_branch .LBB0_833
